# p6-blockhead-prio-before-barrier
# speedup vs baseline: 1.0014x; 1.0014x over previous
; #define PG8_STAGEA(bufoff, goff, voff) PG8_STAGEX(rsA, bufoff, goff, voff)
; #define PG8_STAGEB(bufoff, goff, voff) PG8_STAGEX(rsB, bufoff, goff, voff)
; #define PG8_LDA(dst, b, h) do { _Pragma("unroll") for (int m = 0; m < 4; ++m) _Pragma("unroll") for (int k = 0; k < 2; ++k) dst[m][k] = *(const PG8_LAS bf16x8*)(lds + PG8_SA(b, h) + aoff + m * 2048 + k * 1024); } while (0)
; #define PG8_MMA(ai, bj, At, Bt) do { __builtin_amdgcn_s_setprio(1); _Pragma("unroll") for (int m = 0; m < 4; ++m) _Pragma("unroll") for (int n = 0; n < 2; ++n) _Pragma("unroll") for (int k = 0; k < 2; ++k) \
;         acc[ai][bj][m][n] = __builtin_amdgcn_mfma_f32_16x16x32_bf16(Bt[n][k], At[m][k], acc[ai][bj][m][n], 0, 0, 0); __builtin_amdgcn_s_setprio(0); } while (0)
; #define PG8_WAIT_V(n) asm volatile("s_waitcnt vmcnt(" #n ")" ::: "memory")
; #define PG8_WAIT_L(n) asm volatile("s_waitcnt lgkmcnt(" #n ")" ::: "memory")
; #define PG8_BAR __builtin_amdgcn_s_barrier()
; #define PG8_SCHED __builtin_amdgcn_sched_barrier(0)
; template <class Epi, class Sched, bool ALIGN_EPI = false, bool SP2 = false>
; __device__ __forceinline__ void gemm_phase(PG8_LAS unsigned char* lds, const Gemm g, const Sched& S, const Epi& E) {
;     ...
;         const size_t nA = has_next ? (size_t)nxt.pm * tstep : cA; const size_t nB = has_next ? (size_t)nxt.pn * tstep : cB;
;         for (int t = 0; t < nt; t += 2) {
;             const bool last = (t == nt - 2);
;             if constexpr (Epi::MIDK) { if (t == (nt >> 1)) E.midk(acc, wr, fr, lds); }
;             const size_t a1 = cA + (size_t)(t + 1) * kstep;
;             const size_t a2 = last ? nA : cA + (size_t)(t + 2) * kstep; const size_t b2 = last ? nB : cB + (size_t)(t + 2) * kstep;
;     ...
;             PG8_WAIT_V(8); PG8_WAIT_L(0); PG8_BAR; PG8_MMA(0, 0, At, B0); PG8_MMA(0, 1, At, B1); PG8_BAR; PG8_SCHED;
;             PG8_LDA(At, 0, 1); PG8_STAGEB(PG8_SB(0, 0), b2, voffB); PG8_STAGEB(PG8_SB(0, 1), b2 + hstep, voffB); PG8_STAGEA(PG8_SA(0, 0), a2, voffA);
;             PG8_WAIT_V(8); PG8_WAIT_L(0); PG8_BAR; PG8_MMA(1, 0, At, B0); PG8_MMA(1, 1, At, B1); PG8_BAR; PG8_SCHED;
.LBB0_808:
	s_ashr_i32 s19, s18, 31
	s_lshl_b64 s[30:31], s[18:19], 20
	s_and_b64 s[34:35], s[0:1], exec
	s_cselect_b32 s19, s30, s38
	s_ashr_i32 s21, s20, 31
	s_waitcnt vmcnt(8)
	s_lshl_b64 s[34:35], s[20:21], 20
	s_waitcnt lgkmcnt(0)
	s_and_b64 s[62:63], s[0:1], exec
	s_cselect_b32 s21, s34, s36
	s_setprio 1
	s_barrier
	v_mfma_f32_16x16x32_bf16 v[126:129], v[146:149], v[186:189], v[126:129]
	v_mfma_f32_16x16x32_bf16 v[122:125], v[154:157], v[186:189], v[122:125]
	v_mfma_f32_16x16x32_bf16 v[118:121], v[146:149], v[178:181], v[118:121]
	v_mfma_f32_16x16x32_bf16 v[114:117], v[154:157], v[178:181], v[114:117]
	v_mfma_f32_16x16x32_bf16 v[110:113], v[146:149], v[170:173], v[110:113]
	v_mfma_f32_16x16x32_bf16 v[106:109], v[154:157], v[170:173], v[106:109]
	v_mfma_f32_16x16x32_bf16 v[102:105], v[146:149], v[162:165], v[102:105]
	v_mfma_f32_16x16x32_bf16 v[98:101], v[154:157], v[162:165], v[98:101]
	v_mfma_f32_16x16x32_bf16 v[126:129], v[150:153], v[190:193], v[126:129]
	v_mfma_f32_16x16x32_bf16 v[122:125], v[158:161], v[190:193], v[122:125]
	v_mfma_f32_16x16x32_bf16 v[118:121], v[150:153], v[182:185], v[118:121]
	v_mfma_f32_16x16x32_bf16 v[114:117], v[158:161], v[182:185], v[114:117]
	v_mfma_f32_16x16x32_bf16 v[110:113], v[150:153], v[174:177], v[110:113]
	v_mfma_f32_16x16x32_bf16 v[106:109], v[158:161], v[174:177], v[106:109]
	v_mfma_f32_16x16x32_bf16 v[102:105], v[150:153], v[166:169], v[102:105]
	v_mfma_f32_16x16x32_bf16 v[98:101], v[158:161], v[166:169], v[98:101]
	v_mfma_f32_16x16x32_bf16 v[94:97], v[130:133], v[186:189], v[94:97]
	v_mfma_f32_16x16x32_bf16 v[90:93], v[138:141], v[186:189], v[90:93]
	v_mfma_f32_16x16x32_bf16 v[86:89], v[130:133], v[178:181], v[86:89]
	v_mfma_f32_16x16x32_bf16 v[82:85], v[138:141], v[178:181], v[82:85]
	v_mfma_f32_16x16x32_bf16 v[78:81], v[130:133], v[170:173], v[78:81]
	v_mfma_f32_16x16x32_bf16 v[74:77], v[138:141], v[170:173], v[74:77]
	v_mfma_f32_16x16x32_bf16 v[70:73], v[130:133], v[162:165], v[70:73]
	v_mfma_f32_16x16x32_bf16 v[66:69], v[138:141], v[162:165], v[66:69]
	v_mfma_f32_16x16x32_bf16 v[94:97], v[134:137], v[190:193], v[94:97]
	v_mfma_f32_16x16x32_bf16 v[90:93], v[142:145], v[190:193], v[90:93]
	v_mfma_f32_16x16x32_bf16 v[86:89], v[134:137], v[182:185], v[86:89]
	v_mfma_f32_16x16x32_bf16 v[82:85], v[142:145], v[182:185], v[82:85]
	v_mfma_f32_16x16x32_bf16 v[78:81], v[134:137], v[174:177], v[78:81]
	v_mfma_f32_16x16x32_bf16 v[74:77], v[142:145], v[174:177], v[74:77]
	v_mfma_f32_16x16x32_bf16 v[70:73], v[134:137], v[166:169], v[70:73]
	v_mfma_f32_16x16x32_bf16 v[66:69], v[142:145], v[166:169], v[66:69]
	s_setprio 0
	s_barrier
	s_mov_b32 m0, s47
	s_or_b32 s37, s36, 0x100
	ds_read_b128 v[162:165], v208 offset:16384
	ds_read_b128 v[166:169], v208 offset:17408
	ds_read_b128 v[170:173], v208 offset:18432
	ds_read_b128 v[174:177], v208 offset:19456
	ds_read_b128 v[178:181], v208 offset:20480
	ds_read_b128 v[182:185], v208 offset:21504
	ds_read_b128 v[186:189], v208 offset:22528
	ds_read_b128 v[190:193], v208 offset:23552
	buffer_load_dwordx4 v203, s[40:43], s37 offen lds
	s_mov_b32 m0, s48
	s_mov_b32 s62, s42
	buffer_load_dwordx4 v205, s[40:43], s37 offen lds
	s_or_b32 s37, s36, 0x80100
	s_mov_b32 m0, s49
	s_mov_b32 s63, s43
	buffer_load_dwordx4 v203, s[40:43], s37 offen lds
	s_mov_b32 m0, s50
	s_nop 0
	buffer_load_dwordx4 v205, s[40:43], s37 offen lds
	s_or_b32 s37, s38, 0x100
	s_mov_b32 m0, s46
	s_nop 0
	buffer_load_dwordx4 v202, s[60:63], s37 offen lds
	s_mov_b32 m0, s23
	s_nop 0
	buffer_load_dwordx4 v204, s[60:63], s37 offen lds
	s_waitcnt vmcnt(8)
	s_waitcnt lgkmcnt(0)
	s_setprio 1
	s_barrier
	v_mfma_f32_16x16x32_bf16 v[62:65], v[146:149], v[162:165], v[62:65]
	v_mfma_f32_16x16x32_bf16 v[58:61], v[154:157], v[162:165], v[58:61]
	v_mfma_f32_16x16x32_bf16 v[54:57], v[146:149], v[170:173], v[54:57]
	v_mfma_f32_16x16x32_bf16 v[50:53], v[154:157], v[170:173], v[50:53]
	v_mfma_f32_16x16x32_bf16 v[46:49], v[146:149], v[178:181], v[46:49]
	v_mfma_f32_16x16x32_bf16 v[42:45], v[154:157], v[178:181], v[42:45]
	v_mfma_f32_16x16x32_bf16 v[38:41], v[146:149], v[186:189], v[38:41]
	v_mfma_f32_16x16x32_bf16 v[34:37], v[154:157], v[186:189], v[34:37]
	v_mfma_f32_16x16x32_bf16 v[62:65], v[150:153], v[166:169], v[62:65]
	v_mfma_f32_16x16x32_bf16 v[58:61], v[158:161], v[166:169], v[58:61]
	v_mfma_f32_16x16x32_bf16 v[54:57], v[150:153], v[174:177], v[54:57]
	v_mfma_f32_16x16x32_bf16 v[50:53], v[158:161], v[174:177], v[50:53]
	v_mfma_f32_16x16x32_bf16 v[46:49], v[150:153], v[182:185], v[46:49]
	v_mfma_f32_16x16x32_bf16 v[42:45], v[158:161], v[182:185], v[42:45]
	v_mfma_f32_16x16x32_bf16 v[38:41], v[150:153], v[190:193], v[38:41]
	v_mfma_f32_16x16x32_bf16 v[34:37], v[158:161], v[190:193], v[34:37]
	v_mfma_f32_16x16x32_bf16 v[30:33], v[130:133], v[162:165], v[30:33]
	v_mfma_f32_16x16x32_bf16 v[26:29], v[138:141], v[162:165], v[26:29]
	v_mfma_f32_16x16x32_bf16 v[22:25], v[130:133], v[170:173], v[22:25]
	v_mfma_f32_16x16x32_bf16 v[18:21], v[138:141], v[170:173], v[18:21]
	v_mfma_f32_16x16x32_bf16 v[14:17], v[130:133], v[178:181], v[14:17]
	v_mfma_f32_16x16x32_bf16 v[10:13], v[138:141], v[178:181], v[10:13]
	v_mfma_f32_16x16x32_bf16 v[6:9], v[130:133], v[186:189], v[6:9]
	v_mfma_f32_16x16x32_bf16 v[2:5], v[138:141], v[186:189], v[2:5]
	v_mfma_f32_16x16x32_bf16 v[30:33], v[134:137], v[166:169], v[30:33]
	v_mfma_f32_16x16x32_bf16 v[26:29], v[142:145], v[166:169], v[26:29]
	v_mfma_f32_16x16x32_bf16 v[22:25], v[134:137], v[174:177], v[22:25]
	v_mfma_f32_16x16x32_bf16 v[18:21], v[142:145], v[174:177], v[18:21]
	v_mfma_f32_16x16x32_bf16 v[14:17], v[134:137], v[182:185], v[14:17]
	v_mfma_f32_16x16x32_bf16 v[10:13], v[142:145], v[182:185], v[10:13]
	v_mfma_f32_16x16x32_bf16 v[6:9], v[134:137], v[190:193], v[6:9]
	v_mfma_f32_16x16x32_bf16 v[2:5], v[142:145], v[190:193], v[2:5]
	s_setprio 0
	s_barrier
; #define PG8_STAGEA(bufoff, goff, voff) PG8_STAGEX(rsA, bufoff, goff, voff)
; #define PG8_STAGEB(bufoff, goff, voff) PG8_STAGEX(rsB, bufoff, goff, voff)
; #define PG8_LDA(dst, b, h) do { _Pragma("unroll") for (int m = 0; m < 4; ++m) _Pragma("unroll") for (int k = 0; k < 2; ++k) dst[m][k] = *(const PG8_LAS bf16x8*)(lds + PG8_SA(b, h) + aoff + m * 2048 + k * 1024); } while (0)
; #define PG8_LDB(dst, b, h) do { _Pragma("unroll") for (int n = 0; n < 2; ++n) _Pragma("unroll") for (int k = 0; k < 2; ++k) dst[n][k] = *(const PG8_LAS bf16x8*)(lds + PG8_SB(b, h) + boff + n * 2048 + k * 1024); } while (0)
; #define PG8_MMA(ai, bj, At, Bt) do { __builtin_amdgcn_s_setprio(1); _Pragma("unroll") for (int m = 0; m < 4; ++m) _Pragma("unroll") for (int n = 0; n < 2; ++n) _Pragma("unroll") for (int k = 0; k < 2; ++k) \
;         acc[ai][bj][m][n] = __builtin_amdgcn_mfma_f32_16x16x32_bf16(Bt[n][k], At[m][k], acc[ai][bj][m][n], 0, 0, 0); __builtin_amdgcn_s_setprio(0); } while (0)
; #define PG8_WAIT_V(n) asm volatile("s_waitcnt vmcnt(" #n ")" ::: "memory")
; #define PG8_WAIT_L(n) asm volatile("s_waitcnt lgkmcnt(" #n ")" ::: "memory")
; #define PG8_BAR __builtin_amdgcn_s_barrier()
; #define PG8_SCHED __builtin_amdgcn_sched_barrier(0)
; template <class Epi, class Sched, bool ALIGN_EPI = false, bool SP2 = false>
; __device__ __forceinline__ void gemm_phase(PG8_LAS unsigned char* lds, const Gemm g, const Sched& S, const Epi& E) {
;     ...
;             PG8_LDB(B0, 1, 0); PG8_LDB(B1, 1, 1); PG8_SCHED; PG8_LDA(At, 1, 0); PG8_STAGEA(PG8_SA(0, 1), a2 + hstep, voffA);
;             PG8_WAIT_V(8); PG8_WAIT_L(0); PG8_BAR; PG8_MMA(0, 0, At, B0); PG8_MMA(0, 1, At, B1); PG8_BAR; PG8_SCHED;
;             PG8_LDA(At, 1, 1); PG8_STAGEB(PG8_SB(1, 0), b3, voffB); PG8_STAGEB(PG8_SB(1, 1), b3 + hstep, voffB); PG8_STAGEA(PG8_SA(1, 0), a3, voffA);
;             PG8_WAIT_V(8); PG8_WAIT_L(0); PG8_BAR; PG8_MMA(1, 0, At, B0); PG8_MMA(1, 1, At, B1); PG8_BAR; PG8_SCHED;
	v_add_u32_e32 v130, 0x18000, v207
	v_add_u32_e32 v131, 0x1c000, v207
	ds_read_b128 v[132:135], v130
	ds_read_b128 v[136:139], v130 offset:1024
	ds_read_b128 v[140:143], v130 offset:2048
	ds_read_b128 v[144:147], v130 offset:3072
	ds_read_b128 v[148:151], v131
	ds_read_b128 v[152:155], v131 offset:1024
	ds_read_b128 v[156:159], v131 offset:2048
	ds_read_b128 v[160:163], v131 offset:3072
	s_or_b32 s37, s38, 0x80100
	s_mov_b32 m0, s51
	ds_read_b128 v[164:167], v208 offset:32768
	ds_read_b128 v[168:171], v208 offset:33792
	ds_read_b128 v[172:175], v208 offset:34816
	ds_read_b128 v[176:179], v208 offset:35840
	ds_read_b128 v[180:183], v208 offset:36864
	ds_read_b128 v[184:187], v208 offset:37888
	ds_read_b128 v[188:191], v208 offset:38912
	ds_read_b128 v[212:215], v208 offset:39936
	buffer_load_dwordx4 v202, s[60:63], s37 offen lds
	s_mov_b32 m0, s56
	s_nop 0
	buffer_load_dwordx4 v204, s[60:63], s37 offen lds
	s_waitcnt vmcnt(8)
	s_waitcnt lgkmcnt(0)
	s_setprio 1
	s_barrier
	v_mfma_f32_16x16x32_bf16 v[126:129], v[132:135], v[164:167], v[126:129]
	v_mfma_f32_16x16x32_bf16 v[122:125], v[140:143], v[164:167], v[122:125]
	v_mfma_f32_16x16x32_bf16 v[118:121], v[132:135], v[172:175], v[118:121]
	v_mfma_f32_16x16x32_bf16 v[114:117], v[140:143], v[172:175], v[114:117]
	v_mfma_f32_16x16x32_bf16 v[110:113], v[132:135], v[180:183], v[110:113]
	v_mfma_f32_16x16x32_bf16 v[106:109], v[140:143], v[180:183], v[106:109]
	v_mfma_f32_16x16x32_bf16 v[102:105], v[132:135], v[188:191], v[102:105]
	v_mfma_f32_16x16x32_bf16 v[98:101], v[140:143], v[188:191], v[98:101]
	v_mfma_f32_16x16x32_bf16 v[126:129], v[136:139], v[168:171], v[126:129]
	v_mfma_f32_16x16x32_bf16 v[122:125], v[144:147], v[168:171], v[122:125]
	v_mfma_f32_16x16x32_bf16 v[118:121], v[136:139], v[176:179], v[118:121]
	v_mfma_f32_16x16x32_bf16 v[114:117], v[144:147], v[176:179], v[114:117]
	v_mfma_f32_16x16x32_bf16 v[110:113], v[136:139], v[184:187], v[110:113]
	v_mfma_f32_16x16x32_bf16 v[106:109], v[144:147], v[184:187], v[106:109]
	v_mfma_f32_16x16x32_bf16 v[102:105], v[136:139], v[212:215], v[102:105]
	v_mfma_f32_16x16x32_bf16 v[98:101], v[144:147], v[212:215], v[98:101]
	v_mfma_f32_16x16x32_bf16 v[94:97], v[148:151], v[164:167], v[94:97]
	v_mfma_f32_16x16x32_bf16 v[90:93], v[156:159], v[164:167], v[90:93]
	v_mfma_f32_16x16x32_bf16 v[86:89], v[148:151], v[172:175], v[86:89]
	v_mfma_f32_16x16x32_bf16 v[82:85], v[156:159], v[172:175], v[82:85]
	v_mfma_f32_16x16x32_bf16 v[78:81], v[148:151], v[180:183], v[78:81]
	v_mfma_f32_16x16x32_bf16 v[74:77], v[156:159], v[180:183], v[74:77]
	v_mfma_f32_16x16x32_bf16 v[70:73], v[148:151], v[188:191], v[70:73]
	v_mfma_f32_16x16x32_bf16 v[66:69], v[156:159], v[188:191], v[66:69]
	v_mfma_f32_16x16x32_bf16 v[94:97], v[152:155], v[168:171], v[94:97]
	v_mfma_f32_16x16x32_bf16 v[90:93], v[160:163], v[168:171], v[90:93]
	v_mfma_f32_16x16x32_bf16 v[86:89], v[152:155], v[176:179], v[86:89]
	v_mfma_f32_16x16x32_bf16 v[82:85], v[160:163], v[176:179], v[82:85]
	v_mfma_f32_16x16x32_bf16 v[78:81], v[152:155], v[184:187], v[78:81]
	v_mfma_f32_16x16x32_bf16 v[74:77], v[160:163], v[184:187], v[74:77]
	v_mfma_f32_16x16x32_bf16 v[70:73], v[152:155], v[212:215], v[70:73]
	v_mfma_f32_16x16x32_bf16 v[66:69], v[160:163], v[212:215], v[66:69]
	s_setprio 0
	s_barrier
	s_mov_b32 m0, s57
	s_or_b32 s37, s36, 0x180
	ds_read_b128 v[164:167], v208 offset:49152
	ds_read_b128 v[168:171], v208 offset:50176
	ds_read_b128 v[172:175], v208 offset:51200
	ds_read_b128 v[176:179], v208 offset:52224
	ds_read_b128 v[180:183], v208 offset:53248
	ds_read_b128 v[184:187], v208 offset:54272
	ds_read_b128 v[188:191], v208 offset:55296
	ds_read_b128 v[212:215], v208 offset:56320
	buffer_load_dwordx4 v203, s[40:43], s37 offen lds
	s_mov_b32 m0, s58
	s_nop 0
	buffer_load_dwordx4 v205, s[40:43], s37 offen lds
	s_or_b32 s37, s36, 0x80180
	s_mov_b32 m0, s65
	s_nop 0
	buffer_load_dwordx4 v203, s[40:43], s37 offen lds
	s_mov_b32 m0, s66
	s_nop 0
	buffer_load_dwordx4 v205, s[40:43], s37 offen lds
	s_or_b32 s37, s38, 0x180
	s_mov_b32 m0, s59
	s_nop 0
	buffer_load_dwordx4 v202, s[60:63], s37 offen lds
	s_mov_b32 m0, s64
	s_nop 0
	buffer_load_dwordx4 v204, s[60:63], s37 offen lds
	s_waitcnt vmcnt(8)
	s_waitcnt lgkmcnt(0)
	s_setprio 1
	s_barrier
	v_mfma_f32_16x16x32_bf16 v[62:65], v[132:135], v[164:167], v[62:65]
	v_mfma_f32_16x16x32_bf16 v[58:61], v[140:143], v[164:167], v[58:61]
	v_mfma_f32_16x16x32_bf16 v[54:57], v[132:135], v[172:175], v[54:57]
	v_mfma_f32_16x16x32_bf16 v[50:53], v[140:143], v[172:175], v[50:53]
	v_mfma_f32_16x16x32_bf16 v[46:49], v[132:135], v[180:183], v[46:49]
	v_mfma_f32_16x16x32_bf16 v[42:45], v[140:143], v[180:183], v[42:45]
	v_mfma_f32_16x16x32_bf16 v[38:41], v[132:135], v[188:191], v[38:41]
	v_mfma_f32_16x16x32_bf16 v[34:37], v[140:143], v[188:191], v[34:37]
	v_mfma_f32_16x16x32_bf16 v[62:65], v[136:139], v[168:171], v[62:65]
	v_mfma_f32_16x16x32_bf16 v[58:61], v[144:147], v[168:171], v[58:61]
	v_mfma_f32_16x16x32_bf16 v[54:57], v[136:139], v[176:179], v[54:57]
	v_mfma_f32_16x16x32_bf16 v[50:53], v[144:147], v[176:179], v[50:53]
	v_mfma_f32_16x16x32_bf16 v[46:49], v[136:139], v[184:187], v[46:49]
	v_mfma_f32_16x16x32_bf16 v[42:45], v[144:147], v[184:187], v[42:45]
	v_mfma_f32_16x16x32_bf16 v[38:41], v[136:139], v[212:215], v[38:41]
	v_mfma_f32_16x16x32_bf16 v[34:37], v[144:147], v[212:215], v[34:37]
	v_mfma_f32_16x16x32_bf16 v[30:33], v[148:151], v[164:167], v[30:33]
	v_mfma_f32_16x16x32_bf16 v[26:29], v[156:159], v[164:167], v[26:29]
	v_mfma_f32_16x16x32_bf16 v[22:25], v[148:151], v[172:175], v[22:25]
	v_mfma_f32_16x16x32_bf16 v[18:21], v[156:159], v[172:175], v[18:21]
	v_mfma_f32_16x16x32_bf16 v[14:17], v[148:151], v[180:183], v[14:17]
	v_mfma_f32_16x16x32_bf16 v[10:13], v[156:159], v[180:183], v[10:13]
	v_mfma_f32_16x16x32_bf16 v[6:9], v[148:151], v[188:191], v[6:9]
	v_mfma_f32_16x16x32_bf16 v[2:5], v[156:159], v[188:191], v[2:5]
	v_mfma_f32_16x16x32_bf16 v[30:33], v[152:155], v[168:171], v[30:33]
	v_mfma_f32_16x16x32_bf16 v[26:29], v[160:163], v[168:171], v[26:29]
	v_mfma_f32_16x16x32_bf16 v[22:25], v[152:155], v[176:179], v[22:25]
	v_mfma_f32_16x16x32_bf16 v[18:21], v[160:163], v[176:179], v[18:21]
	v_mfma_f32_16x16x32_bf16 v[14:17], v[152:155], v[184:187], v[14:17]
	v_mfma_f32_16x16x32_bf16 v[10:13], v[160:163], v[184:187], v[10:13]
	v_mfma_f32_16x16x32_bf16 v[6:9], v[152:155], v[212:215], v[6:9]
	v_mfma_f32_16x16x32_bf16 v[2:5], v[160:163], v[212:215], v[2:5]
	s_setprio 0
	s_barrier
	s_add_u32 s38, s38, 0x200
	s_add_u32 s39, s36, 0x200
	s_mov_b32 s71, 0
	s_mov_b64 s[36:37], 0
; #define PG8_STAGEA(bufoff, goff, voff) PG8_STAGEX(rsA, bufoff, goff, voff)
; #define PG8_STAGEB(bufoff, goff, voff) PG8_STAGEX(rsB, bufoff, goff, voff)
; #define PG8_LDA(dst, b, h) do { _Pragma("unroll") for (int m = 0; m < 4; ++m) _Pragma("unroll") for (int k = 0; k < 2; ++k) dst[m][k] = *(const PG8_LAS bf16x8*)(lds + PG8_SA(b, h) + aoff + m * 2048 + k * 1024); } while (0)
; #define PG8_LDB(dst, b, h) do { _Pragma("unroll") for (int n = 0; n < 2; ++n) _Pragma("unroll") for (int k = 0; k < 2; ++k) dst[n][k] = *(const PG8_LAS bf16x8*)(lds + PG8_SB(b, h) + boff + n * 2048 + k * 1024); } while (0)
; #define PG8_MMA(ai, bj, At, Bt) do { __builtin_amdgcn_s_setprio(1); _Pragma("unroll") for (int m = 0; m < 4; ++m) _Pragma("unroll") for (int n = 0; n < 2; ++n) _Pragma("unroll") for (int k = 0; k < 2; ++k) \
;         acc[ai][bj][m][n] = __builtin_amdgcn_mfma_f32_16x16x32_bf16(Bt[n][k], At[m][k], acc[ai][bj][m][n], 0, 0, 0); __builtin_amdgcn_s_setprio(0); } while (0)
; #define PG8_WAIT_V(n) asm volatile("s_waitcnt vmcnt(" #n ")" ::: "memory")
; #define PG8_WAIT_L(n) asm volatile("s_waitcnt lgkmcnt(" #n ")" ::: "memory")
; #define PG8_BAR __builtin_amdgcn_s_barrier()
; #define PG8_SCHED __builtin_amdgcn_sched_barrier(0)
; template <class Epi, class Sched, bool ALIGN_EPI = false, bool SP2 = false>
; __device__ __forceinline__ void gemm_phase(PG8_LAS unsigned char* lds, const Gemm g, const Sched& S, const Epi& E) {
;     ...
;             PG8_LDB(B0, 0, 0); PG8_LDB(B1, 0, 1); PG8_SCHED; PG8_LDA(At, 0, 0); PG8_STAGEA(PG8_SA(1, 1), a1 + hstep, voffA);
;             if (t == 0 && ui > 0) {
; #pragma unroll
;                 for (int a = 0; a < 2; ++a)
; #pragma unroll
;                     for (int b = 0; b < 2; ++b)
; #pragma unroll
;                         for (int m = 0; m < 4; ++m)
; #pragma unroll
;                             for (int n = 0; n < 2; ++n) acc[a][b][m][n] = (f32x4){0.f, 0.f, 0.f, 0.f}; }
;             PG8_WAIT_V(8); PG8_WAIT_L(0); PG8_BAR; PG8_MMA(0, 0, At, B0); PG8_MMA(0, 1, At, B1); PG8_BAR; PG8_SCHED;
;             PG8_LDA(At, 0, 1); PG8_STAGEB(PG8_SB(0, 0), b2, voffB); PG8_STAGEB(PG8_SB(0, 1), b2 + hstep, voffB); PG8_STAGEA(PG8_SA(0, 0), a2, voffA);
;             PG8_WAIT_V(8); PG8_WAIT_L(0); PG8_BAR; PG8_MMA(1, 0, At, B0); PG8_MMA(1, 1, At, B1); PG8_BAR; PG8_SCHED;
.LBB0_809:
	ds_read_b128 v[132:135], v196
	ds_read_b128 v[136:139], v196 offset:1024
	ds_read_b128 v[140:143], v196 offset:2048
	ds_read_b128 v[144:147], v196 offset:3072
	ds_read_b128 v[148:151], v210
	ds_read_b128 v[152:155], v210 offset:1024
	ds_read_b128 v[156:159], v210 offset:2048
	ds_read_b128 v[160:163], v210 offset:3072
	s_add_i32 s72, s38, s36
	s_mov_b32 m0, s67
	s_add_i32 s73, s72, 0x7ff80
	ds_read_b128 v[164:167], v208
	ds_read_b128 v[168:171], v208 offset:1024
	ds_read_b128 v[172:175], v208 offset:2048
	ds_read_b128 v[176:179], v208 offset:3072
	ds_read_b128 v[180:183], v208 offset:4096
	ds_read_b128 v[184:187], v208 offset:5120
	ds_read_b128 v[188:191], v208 offset:6144
	ds_read_b128 v[212:215], v208 offset:7168
	buffer_load_dwordx4 v202, s[60:63], s73 offen lds
	s_mov_b32 m0, s68
	s_nop 0
	buffer_load_dwordx4 v204, s[60:63], s73 offen lds
	s_waitcnt vmcnt(8)
	s_waitcnt lgkmcnt(0)
	s_add_i32 s73, s39, s36
	s_cmp_eq_u32 s71, 28
	s_setprio 1
	s_barrier
	v_mfma_f32_16x16x32_bf16 v[126:129], v[132:135], v[164:167], v[126:129]
	v_mfma_f32_16x16x32_bf16 v[122:125], v[140:143], v[164:167], v[122:125]
	v_mfma_f32_16x16x32_bf16 v[118:121], v[132:135], v[172:175], v[118:121]
	v_mfma_f32_16x16x32_bf16 v[114:117], v[140:143], v[172:175], v[114:117]
	v_mfma_f32_16x16x32_bf16 v[110:113], v[132:135], v[180:183], v[110:113]
	v_mfma_f32_16x16x32_bf16 v[106:109], v[140:143], v[180:183], v[106:109]
	v_mfma_f32_16x16x32_bf16 v[102:105], v[132:135], v[188:191], v[102:105]
	v_mfma_f32_16x16x32_bf16 v[98:101], v[140:143], v[188:191], v[98:101]
	v_mfma_f32_16x16x32_bf16 v[126:129], v[136:139], v[168:171], v[126:129]
	v_mfma_f32_16x16x32_bf16 v[122:125], v[144:147], v[168:171], v[122:125]
	v_mfma_f32_16x16x32_bf16 v[118:121], v[136:139], v[176:179], v[118:121]
	v_mfma_f32_16x16x32_bf16 v[114:117], v[144:147], v[176:179], v[114:117]
	v_mfma_f32_16x16x32_bf16 v[110:113], v[136:139], v[184:187], v[110:113]
	v_mfma_f32_16x16x32_bf16 v[106:109], v[144:147], v[184:187], v[106:109]
	v_mfma_f32_16x16x32_bf16 v[102:105], v[136:139], v[212:215], v[102:105]
	v_mfma_f32_16x16x32_bf16 v[98:101], v[144:147], v[212:215], v[98:101]
	v_mfma_f32_16x16x32_bf16 v[94:97], v[148:151], v[164:167], v[94:97]
	v_mfma_f32_16x16x32_bf16 v[90:93], v[156:159], v[164:167], v[90:93]
	v_mfma_f32_16x16x32_bf16 v[86:89], v[148:151], v[172:175], v[86:89]
	v_mfma_f32_16x16x32_bf16 v[82:85], v[156:159], v[172:175], v[82:85]
	v_mfma_f32_16x16x32_bf16 v[78:81], v[148:151], v[180:183], v[78:81]
	v_mfma_f32_16x16x32_bf16 v[74:77], v[156:159], v[180:183], v[74:77]
	v_mfma_f32_16x16x32_bf16 v[70:73], v[148:151], v[188:191], v[70:73]
	v_mfma_f32_16x16x32_bf16 v[66:69], v[156:159], v[188:191], v[66:69]
	v_mfma_f32_16x16x32_bf16 v[94:97], v[152:155], v[168:171], v[94:97]
	v_mfma_f32_16x16x32_bf16 v[90:93], v[160:163], v[168:171], v[90:93]
	v_mfma_f32_16x16x32_bf16 v[86:89], v[152:155], v[176:179], v[86:89]
	v_mfma_f32_16x16x32_bf16 v[82:85], v[160:163], v[176:179], v[82:85]
	v_mfma_f32_16x16x32_bf16 v[78:81], v[152:155], v[184:187], v[78:81]
	v_mfma_f32_16x16x32_bf16 v[74:77], v[160:163], v[184:187], v[74:77]
	v_mfma_f32_16x16x32_bf16 v[70:73], v[152:155], v[212:215], v[70:73]
	v_mfma_f32_16x16x32_bf16 v[66:69], v[160:163], v[212:215], v[66:69]
	s_setprio 0
	s_barrier
	s_mov_b32 m0, s47
	s_cselect_b32 s73, s21, s73
	ds_read_b128 v[164:167], v208 offset:16384
	ds_read_b128 v[168:171], v208 offset:17408
	ds_read_b128 v[172:175], v208 offset:18432
	ds_read_b128 v[176:179], v208 offset:19456
	ds_read_b128 v[180:183], v208 offset:20480
	ds_read_b128 v[184:187], v208 offset:21504
	ds_read_b128 v[188:191], v208 offset:22528
	ds_read_b128 v[212:215], v208 offset:23552
	buffer_load_dwordx4 v203, s[40:43], s73 offen lds
	s_mov_b32 m0, s48
	s_cselect_b32 s72, s19, s72
	buffer_load_dwordx4 v205, s[40:43], s73 offen lds
	s_add_i32 s74, s73, 0x80000
	s_mov_b32 m0, s49
	s_nop 0
	buffer_load_dwordx4 v203, s[40:43], s74 offen lds
	s_mov_b32 m0, s50
	s_nop 0
	buffer_load_dwordx4 v205, s[40:43], s74 offen lds
	s_mov_b32 m0, s46
	s_nop 0
	buffer_load_dwordx4 v202, s[60:63], s72 offen lds
	s_mov_b32 m0, s23
	s_nop 0
	buffer_load_dwordx4 v204, s[60:63], s72 offen lds
	s_waitcnt vmcnt(8)
	s_waitcnt lgkmcnt(0)
	s_setprio 1
	s_barrier
	v_mfma_f32_16x16x32_bf16 v[62:65], v[132:135], v[164:167], v[62:65]
	v_mfma_f32_16x16x32_bf16 v[58:61], v[140:143], v[164:167], v[58:61]
	v_mfma_f32_16x16x32_bf16 v[54:57], v[132:135], v[172:175], v[54:57]
	v_mfma_f32_16x16x32_bf16 v[50:53], v[140:143], v[172:175], v[50:53]
	v_mfma_f32_16x16x32_bf16 v[46:49], v[132:135], v[180:183], v[46:49]
	v_mfma_f32_16x16x32_bf16 v[42:45], v[140:143], v[180:183], v[42:45]
	v_mfma_f32_16x16x32_bf16 v[38:41], v[132:135], v[188:191], v[38:41]
	v_mfma_f32_16x16x32_bf16 v[34:37], v[140:143], v[188:191], v[34:37]
	v_mfma_f32_16x16x32_bf16 v[62:65], v[136:139], v[168:171], v[62:65]
	v_mfma_f32_16x16x32_bf16 v[58:61], v[144:147], v[168:171], v[58:61]
	v_mfma_f32_16x16x32_bf16 v[54:57], v[136:139], v[176:179], v[54:57]
	v_mfma_f32_16x16x32_bf16 v[50:53], v[144:147], v[176:179], v[50:53]
	v_mfma_f32_16x16x32_bf16 v[46:49], v[136:139], v[184:187], v[46:49]
	v_mfma_f32_16x16x32_bf16 v[42:45], v[144:147], v[184:187], v[42:45]
	v_mfma_f32_16x16x32_bf16 v[38:41], v[136:139], v[212:215], v[38:41]
	v_mfma_f32_16x16x32_bf16 v[34:37], v[144:147], v[212:215], v[34:37]
	v_mfma_f32_16x16x32_bf16 v[30:33], v[148:151], v[164:167], v[30:33]
	v_mfma_f32_16x16x32_bf16 v[26:29], v[156:159], v[164:167], v[26:29]
	v_mfma_f32_16x16x32_bf16 v[22:25], v[148:151], v[172:175], v[22:25]
	v_mfma_f32_16x16x32_bf16 v[18:21], v[156:159], v[172:175], v[18:21]
	v_mfma_f32_16x16x32_bf16 v[14:17], v[148:151], v[180:183], v[14:17]
	v_mfma_f32_16x16x32_bf16 v[10:13], v[156:159], v[180:183], v[10:13]
	v_mfma_f32_16x16x32_bf16 v[6:9], v[148:151], v[188:191], v[6:9]
	v_mfma_f32_16x16x32_bf16 v[2:5], v[156:159], v[188:191], v[2:5]
	v_mfma_f32_16x16x32_bf16 v[30:33], v[152:155], v[168:171], v[30:33]
	v_mfma_f32_16x16x32_bf16 v[26:29], v[160:163], v[168:171], v[26:29]
	v_mfma_f32_16x16x32_bf16 v[22:25], v[152:155], v[176:179], v[22:25]
	v_mfma_f32_16x16x32_bf16 v[18:21], v[160:163], v[176:179], v[18:21]
	v_mfma_f32_16x16x32_bf16 v[14:17], v[152:155], v[184:187], v[14:17]
	v_mfma_f32_16x16x32_bf16 v[10:13], v[160:163], v[184:187], v[10:13]
	v_mfma_f32_16x16x32_bf16 v[6:9], v[152:155], v[212:215], v[6:9]
	v_mfma_f32_16x16x32_bf16 v[2:5], v[160:163], v[212:215], v[2:5]
	s_setprio 0
	s_barrier
;     __device__ bool next(int i, Unit& u) const { const int L = i * G + c; if (L >= 128) return false; u.pm = L; u.pn = L >> 1; return true; }
; #define PG8_STAGEA(bufoff, goff, voff) PG8_STAGEX(rsA, bufoff, goff, voff)
; #define PG8_STAGEB(bufoff, goff, voff) PG8_STAGEX(rsB, bufoff, goff, voff)
; #define PG8_LDA(dst, b, h) do { _Pragma("unroll") for (int m = 0; m < 4; ++m) _Pragma("unroll") for (int k = 0; k < 2; ++k) dst[m][k] = *(const PG8_LAS bf16x8*)(lds + PG8_SA(b, h) + aoff + m * 2048 + k * 1024); } while (0)
; #define PG8_LDB(dst, b, h) do { _Pragma("unroll") for (int n = 0; n < 2; ++n) _Pragma("unroll") for (int k = 0; k < 2; ++k) dst[n][k] = *(const PG8_LAS bf16x8*)(lds + PG8_SB(b, h) + boff + n * 2048 + k * 1024); } while (0)
; #define PG8_MMA(ai, bj, At, Bt) do { __builtin_amdgcn_s_setprio(1); _Pragma("unroll") for (int m = 0; m < 4; ++m) _Pragma("unroll") for (int n = 0; n < 2; ++n) _Pragma("unroll") for (int k = 0; k < 2; ++k) \
;         acc[ai][bj][m][n] = __builtin_amdgcn_mfma_f32_16x16x32_bf16(Bt[n][k], At[m][k], acc[ai][bj][m][n], 0, 0, 0); __builtin_amdgcn_s_setprio(0); } while (0)
; #define PG8_WAIT_V(n) asm volatile("s_waitcnt vmcnt(" #n ")" ::: "memory")
; #define PG8_WAIT_L(n) asm volatile("s_waitcnt lgkmcnt(" #n ")" ::: "memory")
; #define PG8_BAR __builtin_amdgcn_s_barrier()
; #define PG8_SCHED __builtin_amdgcn_sched_barrier(0)
; template <class Epi, class Sched, bool ALIGN_EPI = false, bool SP2 = false>
; __device__ __forceinline__ void gemm_phase(PG8_LAS unsigned char* lds, const Gemm g, const Sched& S, const Epi& E) {
;     ...
;     for (;;) {
;         const bool has_next = S.next(ui + 1, nxt);
;         const size_t nA = has_next ? (size_t)nxt.pm * tstep : cA; const size_t nB = has_next ? (size_t)nxt.pn * tstep : cB;
;         for (int t = 0; t < nt; t += 2) {
;     ...
;             PG8_LDB(B0, 1, 0); PG8_LDB(B1, 1, 1); PG8_SCHED; PG8_LDA(At, 1, 0); PG8_STAGEA(PG8_SA(0, 1), a2 + hstep, voffA);
;             PG8_WAIT_V(8); PG8_WAIT_L(0); PG8_BAR; PG8_MMA(0, 0, At, B0); PG8_MMA(0, 1, At, B1); PG8_BAR; PG8_SCHED;
;             PG8_LDA(At, 1, 1); PG8_STAGEB(PG8_SB(1, 0), b3, voffB); PG8_STAGEB(PG8_SB(1, 1), b3 + hstep, voffB); PG8_STAGEA(PG8_SA(1, 0), a3, voffA);
;             PG8_WAIT_V(8); PG8_WAIT_L(0); PG8_BAR; PG8_MMA(1, 0, At, B0); PG8_MMA(1, 1, At, B1); PG8_BAR; PG8_SCHED;
	ds_read_b128 v[132:135], v130
	ds_read_b128 v[136:139], v130 offset:1024
	ds_read_b128 v[140:143], v130 offset:2048
	ds_read_b128 v[144:147], v130 offset:3072
	ds_read_b128 v[148:151], v131
	ds_read_b128 v[152:155], v131 offset:1024
	ds_read_b128 v[156:159], v131 offset:2048
	ds_read_b128 v[160:163], v131 offset:3072
	s_add_i32 s74, s72, 0x80000
	s_mov_b32 m0, s51
	ds_read_b128 v[164:167], v208 offset:32768
	ds_read_b128 v[168:171], v208 offset:33792
	ds_read_b128 v[172:175], v208 offset:34816
	ds_read_b128 v[176:179], v208 offset:35840
	ds_read_b128 v[180:183], v208 offset:36864
	ds_read_b128 v[184:187], v208 offset:37888
	ds_read_b128 v[188:191], v208 offset:38912
	ds_read_b128 v[212:215], v208 offset:39936
	buffer_load_dwordx4 v202, s[60:63], s74 offen lds
	s_mov_b32 m0, s56
	s_nop 0
	buffer_load_dwordx4 v204, s[60:63], s74 offen lds
	s_waitcnt vmcnt(8)
	s_waitcnt lgkmcnt(0)
	s_setprio 1
	s_barrier
	v_mfma_f32_16x16x32_bf16 v[126:129], v[132:135], v[164:167], v[126:129]
	v_mfma_f32_16x16x32_bf16 v[122:125], v[140:143], v[164:167], v[122:125]
	v_mfma_f32_16x16x32_bf16 v[118:121], v[132:135], v[172:175], v[118:121]
	v_mfma_f32_16x16x32_bf16 v[114:117], v[140:143], v[172:175], v[114:117]
	v_mfma_f32_16x16x32_bf16 v[110:113], v[132:135], v[180:183], v[110:113]
	v_mfma_f32_16x16x32_bf16 v[106:109], v[140:143], v[180:183], v[106:109]
	v_mfma_f32_16x16x32_bf16 v[102:105], v[132:135], v[188:191], v[102:105]
	v_mfma_f32_16x16x32_bf16 v[98:101], v[140:143], v[188:191], v[98:101]
	v_mfma_f32_16x16x32_bf16 v[126:129], v[136:139], v[168:171], v[126:129]
	v_mfma_f32_16x16x32_bf16 v[122:125], v[144:147], v[168:171], v[122:125]
	v_mfma_f32_16x16x32_bf16 v[118:121], v[136:139], v[176:179], v[118:121]
	v_mfma_f32_16x16x32_bf16 v[114:117], v[144:147], v[176:179], v[114:117]
	v_mfma_f32_16x16x32_bf16 v[110:113], v[136:139], v[184:187], v[110:113]
	v_mfma_f32_16x16x32_bf16 v[106:109], v[144:147], v[184:187], v[106:109]
	v_mfma_f32_16x16x32_bf16 v[102:105], v[136:139], v[212:215], v[102:105]
	v_mfma_f32_16x16x32_bf16 v[98:101], v[144:147], v[212:215], v[98:101]
	v_mfma_f32_16x16x32_bf16 v[94:97], v[148:151], v[164:167], v[94:97]
	v_mfma_f32_16x16x32_bf16 v[90:93], v[156:159], v[164:167], v[90:93]
	v_mfma_f32_16x16x32_bf16 v[86:89], v[148:151], v[172:175], v[86:89]
	v_mfma_f32_16x16x32_bf16 v[82:85], v[156:159], v[172:175], v[82:85]
	v_mfma_f32_16x16x32_bf16 v[78:81], v[148:151], v[180:183], v[78:81]
	v_mfma_f32_16x16x32_bf16 v[74:77], v[156:159], v[180:183], v[74:77]
	v_mfma_f32_16x16x32_bf16 v[70:73], v[148:151], v[188:191], v[70:73]
	v_mfma_f32_16x16x32_bf16 v[66:69], v[156:159], v[188:191], v[66:69]
	v_mfma_f32_16x16x32_bf16 v[94:97], v[152:155], v[168:171], v[94:97]
	v_mfma_f32_16x16x32_bf16 v[90:93], v[160:163], v[168:171], v[90:93]
	v_mfma_f32_16x16x32_bf16 v[86:89], v[152:155], v[176:179], v[86:89]
	v_mfma_f32_16x16x32_bf16 v[82:85], v[160:163], v[176:179], v[82:85]
	v_mfma_f32_16x16x32_bf16 v[78:81], v[152:155], v[184:187], v[78:81]
	v_mfma_f32_16x16x32_bf16 v[74:77], v[160:163], v[184:187], v[74:77]
	v_mfma_f32_16x16x32_bf16 v[70:73], v[152:155], v[212:215], v[70:73]
	v_mfma_f32_16x16x32_bf16 v[66:69], v[160:163], v[212:215], v[66:69]
	s_setprio 0
	s_barrier
	s_mov_b32 m0, s57
	s_add_i32 s74, s73, 0x80
	ds_read_b128 v[164:167], v208 offset:49152
	ds_read_b128 v[168:171], v208 offset:50176
	ds_read_b128 v[172:175], v208 offset:51200
	ds_read_b128 v[176:179], v208 offset:52224
	ds_read_b128 v[180:183], v208 offset:53248
	ds_read_b128 v[184:187], v208 offset:54272
	ds_read_b128 v[188:191], v208 offset:55296
	ds_read_b128 v[212:215], v208 offset:56320
	buffer_load_dwordx4 v203, s[40:43], s74 offen lds
	s_mov_b32 m0, s58
	s_add_i32 s73, s73, 0x80080
	buffer_load_dwordx4 v205, s[40:43], s74 offen lds
	s_mov_b32 m0, s65
	s_addk_i32 s72, 0x80
	buffer_load_dwordx4 v203, s[40:43], s73 offen lds
	s_mov_b32 m0, s66
	s_nop 0
	buffer_load_dwordx4 v205, s[40:43], s73 offen lds
	s_mov_b32 m0, s59
	s_nop 0
	buffer_load_dwordx4 v202, s[60:63], s72 offen lds
	s_mov_b32 m0, s64
	s_nop 0
	buffer_load_dwordx4 v204, s[60:63], s72 offen lds
	s_waitcnt vmcnt(8)
	s_waitcnt lgkmcnt(0)
	s_setprio 1
	s_barrier
	v_mfma_f32_16x16x32_bf16 v[62:65], v[132:135], v[164:167], v[62:65]
	v_mfma_f32_16x16x32_bf16 v[58:61], v[140:143], v[164:167], v[58:61]
	v_mfma_f32_16x16x32_bf16 v[54:57], v[132:135], v[172:175], v[54:57]
	v_mfma_f32_16x16x32_bf16 v[50:53], v[140:143], v[172:175], v[50:53]
	v_mfma_f32_16x16x32_bf16 v[46:49], v[132:135], v[180:183], v[46:49]
	v_mfma_f32_16x16x32_bf16 v[42:45], v[140:143], v[180:183], v[42:45]
	v_mfma_f32_16x16x32_bf16 v[38:41], v[132:135], v[188:191], v[38:41]
	v_mfma_f32_16x16x32_bf16 v[34:37], v[140:143], v[188:191], v[34:37]
	v_mfma_f32_16x16x32_bf16 v[62:65], v[136:139], v[168:171], v[62:65]
	v_mfma_f32_16x16x32_bf16 v[58:61], v[144:147], v[168:171], v[58:61]
	v_mfma_f32_16x16x32_bf16 v[54:57], v[136:139], v[176:179], v[54:57]
	v_mfma_f32_16x16x32_bf16 v[50:53], v[144:147], v[176:179], v[50:53]
	v_mfma_f32_16x16x32_bf16 v[46:49], v[136:139], v[184:187], v[46:49]
	v_mfma_f32_16x16x32_bf16 v[42:45], v[144:147], v[184:187], v[42:45]
	v_mfma_f32_16x16x32_bf16 v[38:41], v[136:139], v[212:215], v[38:41]
	v_mfma_f32_16x16x32_bf16 v[34:37], v[144:147], v[212:215], v[34:37]
	v_mfma_f32_16x16x32_bf16 v[30:33], v[148:151], v[164:167], v[30:33]
	v_mfma_f32_16x16x32_bf16 v[26:29], v[156:159], v[164:167], v[26:29]
	v_mfma_f32_16x16x32_bf16 v[22:25], v[148:151], v[172:175], v[22:25]
	v_mfma_f32_16x16x32_bf16 v[18:21], v[156:159], v[172:175], v[18:21]
	v_mfma_f32_16x16x32_bf16 v[14:17], v[148:151], v[180:183], v[14:17]
	v_mfma_f32_16x16x32_bf16 v[10:13], v[156:159], v[180:183], v[10:13]
	v_mfma_f32_16x16x32_bf16 v[6:9], v[148:151], v[188:191], v[6:9]
	v_mfma_f32_16x16x32_bf16 v[2:5], v[156:159], v[188:191], v[2:5]
	v_mfma_f32_16x16x32_bf16 v[30:33], v[152:155], v[168:171], v[30:33]
	v_mfma_f32_16x16x32_bf16 v[26:29], v[160:163], v[168:171], v[26:29]
	v_mfma_f32_16x16x32_bf16 v[22:25], v[152:155], v[176:179], v[22:25]
	v_mfma_f32_16x16x32_bf16 v[18:21], v[160:163], v[176:179], v[18:21]
	v_mfma_f32_16x16x32_bf16 v[14:17], v[152:155], v[184:187], v[14:17]
	v_mfma_f32_16x16x32_bf16 v[10:13], v[160:163], v[184:187], v[10:13]
	v_mfma_f32_16x16x32_bf16 v[6:9], v[152:155], v[212:215], v[6:9]
	v_mfma_f32_16x16x32_bf16 v[2:5], v[160:163], v[212:215], v[2:5]
	s_setprio 0
	s_barrier
	s_add_i32 s71, s71, 2
	s_add_u32 s36, s36, 0x100
	s_addc_u32 s37, s37, 0
	s_cmp_gt_u32 s71, 29
	s_cbranch_scc0 .LBB0_809
	s_and_b64 vcc, exec, s[16:17]
	s_cbranch_vccz .LBB0_812
	s_barrier
